# grid barrier poll loop backs off (extra s_sleep 40 after 12 polls) on top of per-XCD release words
# baseline (speedup 1.0000x reference)
; __global__ void __launch_bounds__(256, 2) mega(P p, int ph_lo, int ph_hi) {
;     ...
;       grid.sync();
.LBB0_1064:
	s_mov_b64 s[6:7], 0
	s_mov_b32 s8, 0
.LBB0_1065:
	s_sleep 5
	s_add_u32 s8, s8, 1
	s_cmp_lt_u32 s8, 12
	s_cbranch_scc1 .Lpoll_fast
	s_sleep 40
.Lpoll_fast:
	global_load_dword v1, v0, s[58:59] sc1
	s_waitcnt vmcnt(0)
	v_cmp_le_u32_e32 vcc, s5, v1
	s_or_b64 s[6:7], vcc, s[6:7]
	s_andn2_b64 exec, exec, s[6:7]
	s_cbranch_execnz .LBB0_1065
	s_getpc_b64 s[98:99]
